# attention: cross-row exchanges of the four tiles software-pipelined (tile t+1 bpermutes issued before tile t consumed)
# speedup vs baseline: 1.0049x; 1.0049x over previous
; __device__ __forceinline__ void attn_unit(Frame& F, int b, int h, int qt, int kb_lo, int nkb, const bf16* QB, const bf16* KB, const bf16* VT, bf16* OUT, float bias2, f32x4* part, float* tpart) {
;     ...
;             for (int st = 0; st < 4; ++st) {
;                 const float sp2 = om[st][3], sp1 = sp2 * om[st][2], sp0 = sp1 * om[st][1]; lt[st] = sp0 * om[st][0];
;                 bt[st][2] *= sp2; bt[st][1] *= sp1; bt[st][0] *= sp0;
;                 const float xa = __shfl_xor(lt[st], 16), xb = __shfl_xor(lt[st], 32), xc = __shfl_xor(lt[st], 48);
;                 X[st] = (g == 0) ? xa * xb * xc : (g == 1) ? xb * xc : (g == 2) ? xa : 1.f;
;                 GT[st] = lt[st] * xa * xb * xc;
;             }
.LBB0_1065:
	s_or_b64 exec, exec, s[4:5]
	v_lshlrev_b32_e32 v110, 2, v218
	v_xor_b32_e32 v135, 64, v110
	v_xor_b32_e32 v136, 0x80, v110
	v_xor_b32_e32 v137, 0xc0, v110
	v_mul_f32_e32 v111, v127, v134
	v_mul_f32_e32 v110, v111, v109
	v_mul_f32_e32 v112, v110, v108
	ds_bpermute_b32 v113, v135, v112
	ds_bpermute_b32 v114, v136, v112
	ds_bpermute_b32 v115, v137, v112
	s_orn2_b64 s[6:7], vcc, s[0:1]
	s_nand_b64 s[16:17], s[0:1], s[38:39]
	v_mul_f32_e32 v109, v128, v133
	v_mul_f32_e32 v108, v109, v107
	v_mul_f32_e32 v133, v108, v106
	ds_bpermute_b32 v134, v135, v133
	ds_bpermute_b32 v138, v136, v133
	ds_bpermute_b32 v139, v137, v133
	s_waitcnt lgkmcnt(3)
	v_mul_f32_e32 v108, v114, v115
	v_cndmask_b32_e64 v116, 1.0, v113, s[6:7]
	v_cndmask_b32_e64 v108, 1.0, v108, s[16:17]
	v_mul_f32_e32 v116, v116, v108
	v_mul_f32_e32 v107, v129, v132
	v_mul_f32_e32 v106, v107, v105
	v_mul_f32_e32 v140, v106, v104
	ds_bpermute_b32 v141, v135, v140
	ds_bpermute_b32 v142, v136, v140
	ds_bpermute_b32 v143, v137, v140
	s_waitcnt lgkmcnt(3)
	v_mul_f32_e32 v106, v138, v139
	v_cndmask_b32_e64 v117, 1.0, v134, s[6:7]
	v_cndmask_b32_e64 v106, 1.0, v106, s[16:17]
	v_mul_f32_e32 v117, v117, v106
	v_mul_f32_e32 v105, v130, v131
	v_mul_f32_e32 v104, v105, v103
	v_mul_f32_e32 v102, v104, v102
	ds_bpermute_b32 v131, v135, v102
	ds_bpermute_b32 v135, v136, v102
	ds_bpermute_b32 v136, v137, v102
	s_waitcnt lgkmcnt(3)
	v_mul_f32_e32 v104, v142, v143
	v_cndmask_b32_e64 v132, 1.0, v141, s[6:7]
	v_cndmask_b32_e64 v104, 1.0, v104, s[16:17]
	v_mul_f32_e32 v132, v132, v104
	s_waitcnt lgkmcnt(0)
	v_mul_f32_e32 v104, v135, v136
	v_cndmask_b32_e64 v103, 1.0, v131, s[6:7]
	v_cndmask_b32_e64 v104, 1.0, v104, s[16:17]
	v_mul_f32_e32 v103, v103, v104
	s_mov_b64 s[4:5], exec
	s_branch .LBB0_1058
